# compression-MLP layer 2 runs on the same CUs right after layer 1 (one grid barrier and one phase fewer per layer); those CUs no longer convert layer-1 weights
# speedup vs baseline: 1.0058x; 1.0044x over previous
; __device__ __forceinline__ int make_tid(int wave0) { int t = wave0 * 64 + (int)__builtin_amdgcn_mbcnt_hi(~0u, __builtin_amdgcn_mbcnt_lo(~0u, 0u)); asm volatile("" : "+v"(t)); return t; }
; #define LAS __attribute__((address_space(3)))
; #define LANEV() (make_tid(wave0) & 63)
; template <class Epi, class Sched, bool ALIGN_EPI = false, bool SP2 = false>
; __device__ __forceinline__ void gemm_phase(PG8_LAS unsigned char* lds, const Gemm g, const Sched& S, const Epi& E, const int wave0) {
;     const int tid = make_tid(wave0), wid = wave0, lane = tid & 63, wr = wid >> 2, wc = wid & 3, fr = lane & 15, fq = lane >> 4;
;     const int K = g.K, nt = K / BK;
;     unsigned voffA[2], voffB[2];
; #pragma unroll
;     for (int i = 0; i < 2; ++i) { int R, C; stage_rc(tid * 16 + i * 8192, R, C); const int Rb = Epi::PERM ? ((R & ~31) + perm32(R & 31)) : R;
;         voffA[i] = (unsigned)(R * K + C) * 2u; voffB[i] = (unsigned)(Rb * K + C) * 2u; }
;     const size_t kstep = (size_t)(BK * 2);
;     const size_t hstep = (size_t)HALF * K * 2;
;     const size_t tstep = 2 * hstep;
;     const unsigned ldsw = (unsigned)wid * 1024u;
;     const int aoff = lds_byte(wr * 64 + fr, fq * 8), boff = lds_byte(wc * 32 + fr, fq * 8);
; __global__ void __launch_bounds__(NTHR, 2) hymba_fwd(KArgs a) {
;     ...
;         const int cfirst = (G > 96) ? 48 : 0;
;         if (s == 6 && l == 0 && bid >= cfirst) {
;             const int lane_ = LANEV();
;             convert_layer(1, PIN(2), PIN(3), PIN(4), PIN(1), PIN(6), PIN(5), PIN(18), PIN(8), PIN(10), PIN(14), PIN(16), ws, (LAS float*)(lds + wave * 16384), (bid - cfirst) * 8 + wave, (G - cfirst) * 8, lane_);
.LBB0_647:
	s_or_b64 exec, exec, s[0:1]
	s_lshr_b32 s5, s57, 6
	s_bfe_u32 s0, s57, 0x30006
	s_lshl_b32 s58, s0, 3
	s_lshl_b32 s89, s0, 10
	s_mul_hi_u32 s0, s5, 0x15555556
	s_lshr_b32 s1, s57, 2
	s_mul_i32 s0, s0, 12
	s_bfe_u32 s3, s57, 0x20006
	s_and_b32 s59, s1, 48
	s_lshr_b32 s1, s57, 3
	s_lshl_b32 s95, s5, 10
	s_sub_i32 s2, s5, s0
	s_or_b32 s4, s3, 8
	s_lshl_b32 s92, s3, 10
	s_and_b32 s6, s57, 0xffffffc0
	s_lshl_b32 s55, s5, 5
	s_and_b32 s60, s1, 0x1fffffe0
	s_add_i32 s61, s89, 0
	s_add_i32 s33, s95, 0
	s_lshl_b32 s0, s2, 3
	s_lshl_b32 s1, s4, 3
	s_lshl_b32 s62, s3, 12
	s_lshl_b32 s63, s2, 10
	s_lshl_b32 s75, s4, 10
	s_lshl_b32 s64, s3, 3
	s_add_i32 s93, s92, 0
	s_cmpk_lt_u32 s57, 0x100
	s_cselect_b64 s[66:67], -1, 0
	s_add_i32 s2, s33, 0x21400
	v_writelane_b32 v253, s2, 6
	s_mul_i32 s2, s5, 0x2080
	s_add_i32 s2, s2, 0
	s_add_i32 s2, s2, 0x11000
	v_writelane_b32 v253, s2, 7
	s_lshl_b32 s2, s72, 7
	v_writelane_b32 v253, s2, 8
	s_lshr_b32 s2, s57, 8
	s_lshl_b32 s7, s2, 6
	s_and_b32 s4, s55, 0x60
	v_writelane_b32 v253, s7, 9
	s_lshl_b32 s7, s2, 13
	s_lshl_b32 s74, s3, 5
	s_cmp_eq_u32 s2, 1
	v_writelane_b32 v253, s7, 10
	s_cselect_b64 s[8:9], -1, 0
	v_writelane_b32 v253, s8, 11
	s_cmp_gt_u32 s3, 1
	s_cselect_b64 s[86:87], -1, 0
	v_writelane_b32 v253, s9, 12
	s_ashr_i32 s88, s72, 31
	s_lshl_b32 s2, s4, 7
	v_writelane_b32 v253, s4, 13
	s_cmpk_gt_i32 s72, 0x60
	v_writelane_b32 v253, s2, 14
	s_cselect_b32 s3, 48, 0
	s_lshl_b32 s2, s5, 14
	s_add_i32 s2, s2, 0
	v_writelane_b32 v253, s2, 15
	s_sub_i32 s2, s72, s3
	s_and_b32 s71, s3, 32
	s_sub_i32 s2, s2, s71
	s_lshl_b32 s71, s2, 3
	s_add_u32 s2, s78, 0x1e741200
	v_writelane_b32 v253, s3, 16
	s_addc_u32 s3, s79, 0
	v_writelane_b32 v253, s2, 17
	s_movk_i32 s85, 0x60
	s_movk_i32 s65, 0x1400
	v_writelane_b32 v253, s3, 18
	s_add_u32 s2, s78, 0x1e741400
	s_addc_u32 s3, s79, 0
	v_writelane_b32 v253, s2, 19
	v_mov_b32_e32 v215, 0
	v_mov_b32_e32 v244, 0x358637bd
	v_writelane_b32 v253, s3, 20
	s_add_u32 s2, s78, 0x1e741500
	s_addc_u32 s3, s79, 0
	v_writelane_b32 v253, s2, 21
	v_mov_b32_e32 v245, 0x260
	v_mov_b32_e32 v247, 1
	v_writelane_b32 v253, s3, 22
	s_add_u32 s2, s78, 0x1e741600
	s_addc_u32 s3, s79, 0
	v_writelane_b32 v253, s2, 23
	v_mov_b32_e32 v249, 0xff800000
	v_mov_b32_e32 v248, 0x461c4000
	v_writelane_b32 v253, s3, 24
	s_add_u32 s2, s78, 0x1e741700
	s_addc_u32 s3, s79, 0
	v_writelane_b32 v253, s2, 25
	v_mov_b32_e32 v252, 0x90
	s_mov_b32 s96, 0xff800000
	v_writelane_b32 v253, s3, 26
	s_add_u32 s2, s78, 0x1e741800
	s_addc_u32 s3, s79, 0
	v_writelane_b32 v253, s2, 27
	s_mov_b32 s97, 0x41000000
	s_movk_i32 s94, 0x200
	v_writelane_b32 v253, s3, 28
	s_add_u32 s2, s78, 0x1e741900
	s_addc_u32 s3, s79, 0
	v_writelane_b32 v253, s2, 29
	s_movk_i32 s84, 0x90
	s_movk_i32 s70, 0x2c00
	v_writelane_b32 v253, s3, 30
	s_add_u32 s2, s78, 0x1e741a00
	s_addc_u32 s3, s79, 0
	v_writelane_b32 v253, s2, 31
	s_mov_b64 s[90:91], 0x580
	s_nop 0
	v_writelane_b32 v253, s3, 32
	s_add_u32 s2, s78, 0x1e741b00
	s_addc_u32 s3, s79, 0
	v_writelane_b32 v253, s2, 33
	s_nop 1
	v_writelane_b32 v253, s3, 34
	s_add_u32 s2, s78, 0x1e741c00
	s_addc_u32 s3, s79, 0
	v_writelane_b32 v253, s2, 35
	s_nop 1
	v_writelane_b32 v253, s3, 36
	s_add_u32 s2, s78, 0x1e741d00
	s_addc_u32 s3, s79, 0
	v_writelane_b32 v253, s2, 37
	s_nop 1
	v_writelane_b32 v253, s3, 38
	s_add_u32 s2, s78, 0x1e741e00
	s_addc_u32 s3, s79, 0
	v_writelane_b32 v253, s2, 39
	s_nop 1
	v_writelane_b32 v253, s3, 40
	s_add_u32 s2, s78, 0x1e741f00
	s_addc_u32 s3, s79, 0
	v_writelane_b32 v253, s2, 41
	s_nop 1
	v_writelane_b32 v253, s3, 42
	s_add_u32 s2, s78, 0x1e742000
	s_addc_u32 s3, s79, 0
	v_writelane_b32 v253, s2, 43
	s_nop 1
; __device__ __forceinline__ int opaque_bid() { int b = blockIdx.x; asm volatile("" : "+s"(b)); return b; }
; #define LAS __attribute__((address_space(3)))
; #define GAS __attribute__((address_space(1)))
; __global__ void __launch_bounds__(NTHR, 2) hymba_fwd(KArgs a) {
;     ...
;     (void)xcd_barrier_post((unsigned*)(ws0 + WS_BAR), (volatile LAS unsigned*)(lds + MISC_OFF) + 8);
;     ...
;     int rep_ = 0;
;     ...
; #pragma nounroll
;     for (int it = 0; it < 28; ++it) {
;         GAS unsigned char* wsg_; asm volatile("s_mov_b64 %0, %1" : "=s"(wsg_) : "s"(ws0)); unsigned char* ws = (unsigned char*)wsg_;
;         const int wave = wave0, bid = opaque_bid();
;     ...
;         const int gw = bid * 8 + wave;
;         const int l = it / 14, s = it % 14;
	v_writelane_b32 v253, s3, 44
	s_add_u32 s2, s78, 0x1e742100
	s_addc_u32 s3, s79, 0
	v_writelane_b32 v253, s2, 45
	s_nop 1
	v_writelane_b32 v253, s3, 46
	s_add_u32 s2, s78, 0x1e742200
	s_addc_u32 s3, s79, 0
	v_writelane_b32 v253, s2, 47
	s_nop 1
	v_writelane_b32 v253, s3, 48
	s_add_u32 s2, s78, 0x1e742300
	s_addc_u32 s3, s79, 0
	v_writelane_b32 v253, s2, 49
	s_nop 1
	v_writelane_b32 v253, s3, 50
	s_add_u32 s2, s78, 0x1e744400
	s_addc_u32 s3, s79, 0
	v_writelane_b32 v253, s2, 51
	s_nop 1
	v_writelane_b32 v253, s3, 52
	s_add_u32 s2, s78, 0x1e744500
	v_writelane_b32 v253, s78, 53
	s_addc_u32 s3, s79, 0
	s_abs_i32 s4, s71
	v_writelane_b32 v253, s79, 54
	v_writelane_b32 v253, s2, 55
	v_cvt_f32_u32_e32 v1, s4
	s_lshl_b32 s0, s0, 1
	v_writelane_b32 v253, s3, 56
	s_abs_i32 s3, s72
	v_cvt_f32_u32_e32 v0, s3
	v_rcp_iflag_f32_e32 v1, v1
	s_mul_i32 s2, s73, s72
	s_mul_i32 s2, s2, s56
	v_rcp_iflag_f32_e32 v0, v0
	v_writelane_b32 v253, s2, 57
	v_writelane_b32 v253, s3, 58
	s_sub_i32 s2, 0, s3
	v_mul_f32_e32 v0, 0x4f7ffffe, v0
	v_cvt_u32_f32_e32 v0, v0
	s_ashr_i32 s77, s76, 31
	s_add_i32 s56, s55, 0xffffff85
	s_add_i32 s57, 0, 0x23e00
	v_readfirstlane_b32 s3, v0
	v_mul_f32_e32 v0, 0x4f7ffffe, v1
	v_cvt_u32_f32_e32 v0, v0
	s_mul_i32 s2, s2, s3
	s_mul_hi_u32 s2, s3, s2
	s_add_i32 s2, s3, s2
	v_writelane_b32 v253, s2, 59
	s_sub_i32 s2, 0, s4
	v_readfirstlane_b32 s3, v0
	s_mul_i32 s2, s2, s3
	s_mul_hi_u32 s2, s3, s2
	v_writelane_b32 v253, s4, 60
	s_add_i32 s2, s3, s2
	v_writelane_b32 v253, s2, 61
	s_mul_hi_i32 s3, s76, 0x300
	s_mul_i32 s2, s76, 0x300
	v_writelane_b32 v253, s2, 62
	v_mbcnt_lo_u32_b32 v0, -1, 0
	v_mbcnt_hi_u32_b32 v0, -1, v0
	v_writelane_b32 v253, s3, 63
	s_mul_hi_i32 s3, s76, 0x60
	s_mul_i32 s2, s76, 0x60
	v_writelane_b32 v254, s2, 0
	s_add_i32 s69, s61, 0x4000
	s_movk_i32 s73, 0x300
	v_writelane_b32 v254, s3, 1
	s_mul_hi_i32 s3, s76, 0x1400
	s_mul_i32 s2, s76, 0x1400
	v_writelane_b32 v254, s2, 2
	v_add_u32_e32 v246, s6, v0
	s_add_i32 s82, s33, 0x2000
	v_writelane_b32 v254, s3, 3
	v_writelane_b32 v254, s6, 4
	v_writelane_b32 v254, s5, 5
	s_add_i32 s2, s5, s76
	v_writelane_b32 v254, s2, 6
	s_add_i32 s2, s61, 0x8000
	v_writelane_b32 v254, s2, 7
	s_add_i32 s2, s33, 0x3000
	v_writelane_b32 v254, s2, 8
	s_add_i32 s2, s33, 0x1000
	v_writelane_b32 v254, s2, 9
	s_add_i32 s2, 0, 0x23e20
	v_writelane_b32 v254, s2, 10
	s_add_i32 s2, 0, 0x23e24
	v_writelane_b32 v254, s2, 11
	v_writelane_b32 v254, s0, 12
	s_mov_b32 s2, s72
	s_add_i32 s83, s33, 0x6000
	v_writelane_b32 v254, s1, 13
	s_lshl_b32 s0, s1, 1
	v_writelane_b32 v254, s0, 14
	s_mov_b32 s6, 0
	s_mov_b64 s[78:79], 0x80
	v_writelane_b32 v254, s1, 15
	s_lshl_b64 s[0:1], s[76:77], 8
	v_writelane_b32 v254, s0, 16
	s_nop 1
	v_writelane_b32 v254, s1, 17
	s_mov_b32 s0, s76
	v_writelane_b32 v254, s0, 18
	s_nop 1
	v_writelane_b32 v254, s1, 19
	s_lshl_b64 s[0:1], s[76:77], 9
	v_writelane_b32 v254, s0, 20
	s_mov_b64 s[76:77], 0x540
	s_nop 0
	v_writelane_b32 v254, s1, 21
	v_writelane_b32 v254, s2, 22
	s_mov_b64 s[0:1], 0x740
	s_nop 0
	v_writelane_b32 v254, s3, 23
	v_writelane_b32 v254, s52, 24
	s_nop 1
	v_writelane_b32 v254, s53, 25
	v_writelane_b32 v254, s55, 26
	v_writelane_b32 v254, s58, 27
	v_writelane_b32 v254, s59, 28
	v_writelane_b32 v254, s60, 29
	v_writelane_b32 v254, s61, 30
	v_writelane_b32 v254, s62, 31
	v_writelane_b32 v254, s63, 32
	v_writelane_b32 v254, s64, 33
	v_writelane_b32 v254, s66, 34
	s_nop 1
	v_writelane_b32 v254, s67, 35
	v_writelane_b32 v254, s74, 36
	v_writelane_b32 v254, s86, 37
	s_nop 1
	v_writelane_b32 v254, s87, 38
	v_writelane_b32 v254, s88, 39
	v_writelane_b32 v254, s56, 40
	v_writelane_b32 v254, s57, 41
	v_writelane_b32 v254, s69, 42
	s_branch .LBB0_651

; #define GRID_BAR() do { XcdBarrier xb_; xb_.bar = (unsigned*)(ws0 + WS_BAR); xb_.x = xb_xcc_id(); xb_.st = (volatile LAS unsigned*)(lds + MISC_OFF) + 8; xcd_barrier(xb_); } while (0)
; #define LANEV() (make_tid(wave0) & 63)
; __global__ void __launch_bounds__(NTHR, 2) hymba_fwd(KArgs a) {
;     ...
;         const int l = it / 14, s = it % 14;
;         int gid0 = 0, ng = 0, f = 0;
;         bf16_t* hn = (bf16_t*)(ws + WS_HN);
;         bf16_t* P = (bf16_t*)(ws + WS_ACT);
;     ...
;         if (s == 0) { norm_rows_bf16((l == 0) ? PIN(0) : POUT, PIN(1) + (size_t)(l * 2 + 0) * DM, hn, gw, NGW, LANEV()); GRID_BAR(); }
;         else if (s == 3) { norm_rows_bf16(POUT, PIN(5) + (size_t)l * DM, hn, gw, NGW, LANEV()); GRID_BAR(); }
;         else if (s == 11) { norm_rows_bf16(POUT, PIN(1) + (size_t)(l * 2 + 1) * DM, hn, gw, NGW, LANEV()); GRID_BAR(); }
;     ...
;         if (s == 8) { cmp_phase(lds, P, (const bf16_t*)(ws + WS_KC), (const bf16_t*)(ws + WS_VC), (bf16_t*)(ws + WS_OCMP), (unsigned long long*)(ws + WS_MASK), G, wave0); GRID_BAR(); }
;     ...
;         GRID_BAR();
;     ...
;         if (s == 0 || s == 3 || s == 11) continue;
;     ...
;         else if (s == 1) { gid0 = 0; ng = 1; f = 0; }
;     ...
;         if (s == 1 || s == 12) ng = 2;
;     ...
;         else if (s == 2) { gid0 = 1; ng = 1; f = 0; }
;         else if (s == 4) { gid0 = 2; ng = 1; }
;         else if (s == 6) { gid0 = 3; ng = 4; }
;         else if (s == 7) { gid0 = 7; ng = 2; }
;         else if (s == 10) { gid0 = 9; ng = 1; }
;         else if (s == 12) { gid0 = 0; ng = 1; f = 1; }
;         else { gid0 = 1; ng = 1; f = 1; }
.LBB0_651:
	v_readlane_b32 s2, v253, 53
	v_readlane_b32 s3, v253, 54
	s_mov_b64 s[8:9], s[2:3]
	v_readlane_b32 s2, v253, 0
	s_nop 1
	v_writelane_b32 v254, s2, 43
	v_sub_co_u32_e64 v0, s[2:3], s6, 14
	s_and_b64 s[2:3], s[2:3], exec
	v_readfirstlane_b32 s2, v0
	s_cselect_b32 s7, s6, s2
	s_cmp_eq_u32 s7, 7
	s_cselect_b32 s7, 0, s7
	s_cmp_eq_u32 s7, 0
	s_cselect_b64 s[2:3], -1, 0
	s_and_b32 s4, s7, 7
	s_cmp_eq_u32 s4, 3
	s_cselect_b64 s[4:5], -1, 0
	s_or_b64 s[2:3], s[2:3], s[4:5]
	s_and_b64 vcc, exec, s[2:3]
	s_cbranch_vccnz .LBB0_650
	s_cmp_gt_u32 s6, 13
	s_cselect_b64 s[2:3], -1, 0
	v_writelane_b32 v254, s2, 44
	s_nop 1
	v_writelane_b32 v254, s3, 45
	s_add_u32 s2, s8, 0x56c1000
	s_addc_u32 s3, s9, 0
	v_writelane_b32 v254, s2, 46
	s_nop 1
	v_writelane_b32 v254, s3, 47
	s_add_u32 s2, s8, 0x96c1000
	s_addc_u32 s3, s9, 0
	v_writelane_b32 v254, s2, 48
	s_cmp_lt_i32 s7, 7
	s_nop 0
	v_writelane_b32 v254, s3, 49
	v_writelane_b32 v254, s8, 50
	s_nop 1
	v_writelane_b32 v254, s9, 51
	v_writelane_b32 v254, s7, 52
	v_writelane_b32 v254, s6, 53
	s_cbranch_scc1 .LBB0_753
	s_cmp_gt_i32 s7, 8
	s_cbranch_scc0 .LBB0_754
	s_mov_b64 s[4:5], 0
	v_writelane_b32 v254, s4, 54
	s_mov_b64 s[2:3], -1
	s_cmp_gt_i32 s7, 9
	v_writelane_b32 v254, s5, 55
	s_mov_b64 s[4:5], -1
	s_cbranch_scc0 .LBB0_663
	v_readlane_b32 s6, v254, 52
	s_cmp_gt_i32 s6, 11
	s_mov_b64 s[6:7], 0
	v_writelane_b32 v254, s6, 54
	s_mov_b64 s[14:15], 0
	s_nop 0
	v_writelane_b32 v254, s7, 55
	s_cbranch_scc0 .LBB0_659
	v_readlane_b32 s4, v254, 52
	s_cmp_eq_u32 s4, 12
	s_mov_b64 s[4:5], -1
	s_cbranch_scc0 .LBB0_658
	s_mov_b64 s[4:5], 0

; __global__ void __launch_bounds__(NTHR, 2) hymba_fwd(KArgs a) {
;     ...
;         else if (s == 6) { gid0 = 3; ng = 4; }
;         else if (s == 7) { gid0 = 7; ng = 2; }
.LBB0_960:
	s_mov_b32 s69, 6
	s_mov_b32 s68, 3
	s_branch .LBB0_962

; #define GAS __attribute__((address_space(1)))
; __device__ __forceinline__ GemmDesc make_gemm(int id, int l, int f, unsigned char* ws) {
;     ...
;     case 7: case 8: {
;         const int kv = id - 7;
;         d.M = 4096; d.A = (const bf16_t*)(ws + (kv ? WS_HIDV : WS_HIDK)); d.Bt = (const bf16_t*)(ws + WS_W2 + (size_t)(l * 2 + kv) * SZ_W2); d.N = 256; d.K = 256; d.rot = 16 * kv;
;         d.e.kind = EK_BF16; d.e.o0 = (GAS bf16_t*)((bf16_t*)(ws + (kv ? WS_VC : WS_KC))); d.e.ldc = 64; d.e.ncols = 64; break; }
; __global__ void __launch_bounds__(NTHR, 2) hymba_fwd(KArgs a) {
;     ...
;             pg8::StaticOrder S; S.init(d.M, d.N, G, (int)((bid + d.rot) % G));
.LBB0_985:
	s_andn2_b64 vcc, exec, s[2:3]
	s_cbranch_vccnz .LBB0_1241
	s_add_i32 s5, s4, -7
	s_cmp_eq_u32 s5, 0
	s_mov_b32 s2, 0x1bec1000
	s_cselect_b32 s2, s2, 0x1c0c1000
	s_add_u32 s36, s8, s2
	s_addc_u32 s37, s9, 0
	s_add_i32 s2, s5, s30
	s_ashr_i32 s3, s2, 31
	s_lshl_b64 s[2:3], s[2:3], 17
	v_readlane_b32 s6, v254, 62
	s_add_u32 s38, s6, s2
	v_readlane_b32 s2, v254, 60
	s_addc_u32 s39, s2, s3
	s_lshl_b32 s5, s5, 4
	s_add_i32 s5, s5, 16
	s_movk_i32 s22, 0x100
	s_mov_b32 s20, 1
	s_mov_b32 s35, 16
	s_mov_b64 s[2:3], 0

; #define LAS __attribute__((address_space(3)))
; #define LANEV() (make_tid(wave0) & 63)
; __device__ __forceinline__ void convert_layer(int l, const float* w_gate, const float* w_up, const float* w_down, const float* ffn_g, const float* w_in, const float* mix_g, ...
; #pragma nounroll
;     for (int f = 0; f < 2; ++f) {
;         const int lf = l * 2 + f; const size_t wo = (size_t)lf * DM * FF;
;         transpose_mat(w_gate + wo, DM, FF, FF, (bf16_t*)(ws + WS_WGU + lf * SZ_WGU), 256, 0, scr, gw, NGW, lane, ffn_g + (size_t)lf * DM);
;         transpose_mat(w_up + wo, DM, FF, FF, (bf16_t*)(ws + WS_WGU + lf * SZ_WGU), 256, 128, scr, gw, NGW, lane, ffn_g + (size_t)lf * DM);
;         transpose_mat(w_down + wo, FF, DM, DM, (bf16_t*)(ws + WS_WD + lf * SZ_WD), 128, 0, scr, gw, NGW, lane);
;     }
;     transpose_mat(w_in + (size_t)l * DM * NIN, DM, NIN, NPJ, (bf16_t*)(ws + WS_WIN + l * SZ_WIN), 128, 0, scr, gw, NGW, lane, mix_g + (size_t)l * DM);
;     transpose_mat(w_out + (size_t)l * DM * DM, DM, DM, DM, (bf16_t*)(ws + WS_WOUT + l * SZ_WOUT), 128, 0, scr, (gw + 512) % NGW, NGW, lane);
;     transpose_mat(w_uq + (size_t)l * 256 * 384, 256, 384, 512, (bf16_t*)(ws + WS_WUQ + l * SZ_WUQ), 128, 0, scr, (gw + 1024) % NGW, NGW, lane);
;     transpose_mat(w_ukv + (size_t)l * 128 * 512, 128, 512, 512, (bf16_t*)(ws + WS_WUKV + l * SZ_WUKV), 128, 0, scr, (gw + 1200) % NGW, NGW, lane);
; #pragma nounroll
;     for (int kv = 0; kv < 2; ++kv) {
;         transpose_mat(w1 + (size_t)(l * 2 + kv) * 2048 * 256, 2048, 256, 256, (bf16_t*)(ws + WS_W1 + (l * 2 + kv) * SZ_W1), 128, 0, scr, (gw + 1400 + 100 * kv) % NGW, NGW, lane);
;         transpose_mat(w2 + (size_t)(l * 2 + kv) * 256 * 64, 256, 64, 256, (bf16_t*)(ws + WS_W2 + (l * 2 + kv) * SZ_W2), 128, 0, scr, (gw + 1600 + 40 * kv) % NGW, NGW, lane);
;     }
; }
; __global__ void __launch_bounds__(NTHR, 2) hymba_fwd(KArgs a) {
;     ...
;         const int cfirst = (G > 96) ? 48 : 0;
;         if (s == 6 && l == 0 && bid >= cfirst) {
;             const int lane_ = LANEV();
;             convert_layer(1, PIN(2), PIN(3), PIN(4), PIN(1), PIN(6), PIN(5), PIN(18), PIN(8), PIN(10), PIN(14), PIN(16), ws, (LAS float*)(lds + wave * 16384), (bid - cfirst) * 8 + wave, (G - cfirst) * 8, lane_);
.LBB0_2445:
	v_readlane_b32 s2, v254, 52
	s_cmp_lg_u32 s2, 6
	v_readlane_b32 s4, v253, 16
	v_readlane_b32 s6, v254, 43
	s_cselect_b64 s[2:3], -1, 0
	s_cmp_lt_i32 s6, s4
	s_cselect_b64 s[4:5], -1, 0
	s_or_b64 s[2:3], s[2:3], s[4:5]
	s_lshr_b32 s4, s71, 3
	v_readlane_b32 s5, v253, 16
	s_nop 3
	s_add_i32 s4, s4, s5
	s_cmp_ge_i32 s6, s4
	s_cselect_b64 s[4:5], -1, 0
	s_or_b64 s[2:3], s[2:3], s[4:5]
	v_readlane_b32 s4, v254, 44
	v_readlane_b32 s5, v254, 45
	s_or_b64 s[2:3], s[2:3], s[4:5]
	v_readlane_b32 s34, v253, 17
	v_readlane_b32 s36, v253, 19
	v_readlane_b32 s38, v253, 21
	v_readlane_b32 s40, v253, 23
	v_readlane_b32 s42, v253, 25
	v_readlane_b32 s44, v253, 27
	v_readlane_b32 s46, v253, 29
	v_readlane_b32 s48, v253, 31
	v_readlane_b32 s50, v253, 33
	v_readlane_b32 s52, v253, 35
	v_readlane_b32 s56, v253, 37
	v_readlane_b32 s68, v253, 39
	s_andn2_b64 vcc, exec, s[2:3]
	v_readlane_b32 s55, v254, 26
	v_readlane_b32 s58, v254, 27
	v_readlane_b32 s59, v254, 28
	v_readlane_b32 s60, v254, 29
	v_readlane_b32 s61, v254, 30
	v_readlane_b32 s62, v254, 31
	v_readlane_b32 s63, v254, 32
	v_readlane_b32 s64, v254, 33
	v_readlane_b32 s35, v253, 18
	v_readlane_b32 s37, v253, 20
	v_readlane_b32 s39, v253, 22
	v_readlane_b32 s41, v253, 24
	v_readlane_b32 s43, v253, 26
	v_readlane_b32 s45, v253, 28
	v_readlane_b32 s47, v253, 30
	v_readlane_b32 s49, v253, 32
	v_readlane_b32 s51, v253, 34
	v_readlane_b32 s53, v253, 36
	v_readlane_b32 s57, v253, 38
	v_readlane_b32 s69, v253, 40
	s_movk_i32 s65, 0x1400
	s_movk_i32 s84, 0x90
	s_cbranch_vccz .LBB0_2963
	v_mov_b32_e32 v17, v246
	global_load_dwordx4 v[0:3], v215, s[8:9] offset:3080
	global_load_dwordx4 v[8:11], v215, s[8:9] offset:3096
	global_load_dwordx4 v[4:7], v215, s[8:9] offset:3112
	s_waitcnt lgkmcnt(0)
	global_load_dwordx2 v[20:21], v215, s[8:9] offset:3136
	global_load_dwordx2 v[22:23], v215, s[8:9] offset:3216
	global_load_dwordx2 v[18:19], v215, s[8:9] offset:3152
	global_load_dwordx2 v[12:13], v215, s[8:9] offset:3184
	global_load_dwordx2 v[14:15], v215, s[8:9] offset:3200
	v_bfe_u32 v16, v17, 5, 1
	v_mov_b32_e32 v26, 0x108
	s_movk_i32 s3, 0x84
	v_mad_u32_u24 v80, v16, s3, v26
	v_mov_b32_e32 v26, 0x210
	v_mad_u32_u24 v81, v16, s3, v26
	v_mov_b32_e32 v26, 0x318
	v_mad_u32_u24 v82, v16, s3, v26
	v_mov_b32_e32 v26, 0x420
	v_mad_u32_u24 v45, v16, s3, v26
	v_mov_b32_e32 v26, 0x528
	v_mad_u32_u24 v83, v16, s3, v26
	v_mov_b32_e32 v26, 0x630
	v_mad_u32_u24 v84, v16, s3, v26
	v_mov_b32_e32 v26, 0x738
	v_mad_u32_u24 v85, v16, s3, v26
	v_mov_b32_e32 v26, 0x840
	v_mad_u32_u24 v50, v16, s3, v26
	v_mov_b32_e32 v26, 0x948
	v_mad_u32_u24 v86, v16, s3, v26
	v_mov_b32_e32 v26, 0xa50
	v_mad_u32_u24 v87, v16, s3, v26
	v_mov_b32_e32 v26, 0xb58
	v_mad_u32_u24 v88, v16, s3, v26
	v_mov_b32_e32 v26, 0xc60
	v_mad_u32_u24 v55, v16, s3, v26
	v_mov_b32_e32 v26, 0xd68
	v_mad_u32_u24 v89, v16, s3, v26
	v_mov_b32_e32 v26, 0xe70
	v_mad_u32_u24 v90, v16, s3, v26
	v_mov_b32_e32 v26, 0xf78
	v_mad_u32_u24 v91, v16, s3, v26
	v_mov_b32_e32 v26, 0x1080
	v_mad_u32_u24 v60, v16, s3, v26
	v_mov_b32_e32 v26, 0x1188
	v_mad_u32_u24 v92, v16, s3, v26
	v_mov_b32_e32 v26, 0x1290
	v_mad_u32_u24 v93, v16, s3, v26
	v_mov_b32_e32 v26, 0x1398
	v_mad_u32_u24 v94, v16, s3, v26
	v_mov_b32_e32 v26, 0x14a0
	v_readlane_b32 s2, v253, 16
	v_mad_u32_u24 v65, v16, s3, v26
	v_mov_b32_e32 v26, 0x15a8
	s_sub_i32 s2, s6, s2
	v_mad_u32_u24 v95, v16, s3, v26
	v_mov_b32_e32 v26, 0x16b0
	s_lshl_b32 s22, s2, 3
	v_readlane_b32 s2, v254, 5
	v_mad_u32_u24 v96, v16, s3, v26
	v_mov_b32_e32 v26, 0x17b8
	s_add_i32 s22, s22, s2
	v_mad_u32_u24 v97, v16, s3, v26
	v_mov_b32_e32 v26, 0x18c0
	v_and_b32_e32 v25, 31, v17
	v_bfe_u32 v38, v17, 3, 3
	v_lshlrev_b32_e32 v17, 3, v17
	s_add_u32 s23, s8, 0x181000
	v_mad_u32_u24 v70, v16, s3, v26
	v_mov_b32_e32 v26, 0x19c8
	v_and_b32_e32 v24, 56, v17
	v_mad_u32_u24 v98, v16, s3, v26
	v_mov_b32_e32 v26, 0x1ad0
	s_addc_u32 s24, s9, 0
	v_readlane_b32 s2, v253, 15
	v_lshlrev_b32_e32 v17, 2, v38
	v_mad_u32_u24 v73, v16, s3, v26
	v_mul_u32_u24_e32 v26, 0x84, v24
	s_cmpk_lt_u32 s22, 0x580
	s_mov_b64 s[4:5], s[8:9]
	v_lshlrev_b32_e32 v214, 1, v24
	v_add3_u32 v74, s2, v26, v17
	s_cselect_b64 s[8:9], -1, 0
	s_cmpk_gt_u32 s22, 0x57f
	v_lshl_add_u64 v[26:27], s[4:5], 0, v[214:215]
	s_mov_b64 s[4:5], 0x2d81000
	v_lshl_add_u32 v39, v25, 2, s2
	v_mul_u32_u24_e32 v40, 0x84, v16
	v_or_b32_e32 v41, 2, v16
	v_or_b32_e32 v42, 4, v16
	v_or_b32_e32 v43, 6, v16
	v_or_b32_e32 v44, 8, v16
	v_or_b32_e32 v46, 10, v16
	v_or_b32_e32 v47, 12, v16
	v_or_b32_e32 v48, 14, v16
	v_or_b32_e32 v49, 16, v16
	v_or_b32_e32 v51, 18, v16
	v_or_b32_e32 v52, 20, v16
	v_or_b32_e32 v53, 22, v16
	v_or_b32_e32 v54, 24, v16
	v_or_b32_e32 v56, 26, v16
	v_or_b32_e32 v57, 28, v16
	v_or_b32_e32 v58, 30, v16
	v_or_b32_e32 v59, 32, v16
	v_or_b32_e32 v61, 34, v16
	v_or_b32_e32 v62, 36, v16
	v_or_b32_e32 v63, 38, v16
	v_or_b32_e32 v64, 40, v16
	v_or_b32_e32 v66, 42, v16
	v_or_b32_e32 v67, 44, v16
	v_or_b32_e32 v68, 46, v16
	v_or_b32_e32 v69, 48, v16
	v_or_b32_e32 v71, 50, v16
	v_or_b32_e32 v72, 52, v16
	s_cselect_b64 s[10:11], -1, 0
	s_waitcnt vmcnt(0)
	v_cmp_ne_u64_e64 s[2:3], 0, v[0:1]
	v_or_b32_e32 v75, 54, v16
	v_or_b32_e32 v76, 56, v16
	v_or_b32_e32 v77, 58, v16
	v_or_b32_e32 v78, 60, v16
	v_or_b32_e32 v79, 62, v16
	v_lshl_add_u64 v[26:27], v[26:27], 0, s[4:5]
	v_mov_b32_e32 v17, v215
	v_mul_u32_u24_e32 v99, 0xb00, v38
	s_mov_b64 s[14:15], 2
	s_mov_b64 s[12:13], -1
	s_branch .LBB0_2448
